# attention unit epilogue: stage O through per-wave LDS, 4 full-line dwordx4 stores per lane instead of 32 short stores (on top of 4-bit K swizzle)
# baseline (speedup 1.0000x reference)
; DEVFI unsigned f2bf(float f) { unsigned u = __builtin_bit_cast(unsigned, f); return (u + 0x7fffu + ((u >> 16) & 1u)) >> 16; }
; DEVFI int crow(int r, int hi) { return (r & 3) + 8 * (r >> 2) + 4 * hi; }
; template <int DQK, int DV, bool PRE = false>
; DEVFI void attn_unit(const bf16_t* __restrict__ Qb, int ldq, const bf16_t* __restrict__ Kh, int ldk, const bf16_t* __restrict__ Vh, int ldv,
;                      bf16_t* __restrict__ Ob, int ldo, int seq, float scale, char* lds) {
;     ...
;     if (hi == 0) li_l[r32] = l_reg; asm volatile("s_waitcnt lgkmcnt(0)" ::: "memory");
;     float rli[16];
; #pragma unroll
;     for (int r = 0; r < 16; ++r) rli[r] = __builtin_amdgcn_rcpf(li_l[crow(r, hi)]);
;     bf16_t* Ow = Ob + (size_t)(wid * QBLK) * ldo;
; #pragma unroll
;     for (int r = 0; r < 16; ++r) { const int orow = crow(r, hi);
; #pragma unroll
;         for (int d0 = 0; d0 < NCB; ++d0) Ow[(size_t)orow * ldo + d0 * 32 + r32] = (bf16_t)f2bf(o[d0][r] * rli[r]); }
;     __syncthreads();
.LBB0_1139:
	s_or_b64 exec, exec, s[0:1]
	s_waitcnt lgkmcnt(0)
	v_add_u32_e32 v8, v153, v150
	ds_read_b128 v[0:3], v8 offset:49152
	ds_read_b128 v[4:7], v8 offset:49184
	s_lshl_b64 s[0:1], s[12:13], 10
	s_add_u32 s0, s30, s0
	s_addc_u32 s1, s31, s1
	s_waitcnt lgkmcnt(1)
	v_rcp_f32_e32 v9, v0
	v_rcp_f32_e32 v10, v1
	v_rcp_f32_e32 v11, v2
	v_rcp_f32_e32 v13, v3
	ds_read_b128 v[0:3], v8 offset:49216
	s_waitcnt lgkmcnt(1)
	v_rcp_f32_e32 v46, v4
	v_rcp_f32_e32 v47, v5
	v_rcp_f32_e32 v48, v6
	v_rcp_f32_e32 v49, v7
	ds_read_b128 v[4:7], v8 offset:49248
	s_add_u32 s0, s0, s14
	v_ashrrev_i32_e32 v153, 31, v152
	s_addc_u32 s1, s1, s15
	s_waitcnt lgkmcnt(1)
	v_rcp_f32_e32 v8, v0
	v_rcp_f32_e32 v50, v1
	v_lshlrev_b64 v[0:1], 10, v[152:153]
	s_waitcnt lgkmcnt(0)
	v_rcp_f32_e32 v53, v4
	v_rcp_f32_e32 v54, v5
	v_lshl_add_u64 v[0:1], s[0:1], 0, v[0:1]
	v_lshlrev_b32_e32 v4, 1, v151
	v_mov_b32_e32 v5, v12
	v_rcp_f32_e32 v51, v2
	v_rcp_f32_e32 v52, v3
	v_lshlrev_b32_e32 v2, 12, v164
	v_lshl_add_u64 v[0:1], v[0:1], 0, v[4:5]
	v_mov_b32_e32 v3, v12
	v_lshl_add_u64 v[0:1], v[0:1], 0, v[2:3]
	v_lshlrev_b32_e32 v60, 7, v152
	v_lshl_add_u32 v60, v164, 9, v60
	v_add_u32_e32 v60, 0x10000, v60
	v_lshl_add_u32 v61, v151, 4, v60
	v_lshl_add_u32 v60, v151, 1, v60
	v_lshrrev_b32_e32 v64, 3, v151
	v_and_b32_e32 v65, 7, v151
	v_lshlrev_b32_e32 v64, 10, v64
	v_lshl_add_u32 v64, v65, 4, v64
	v_lshlrev_b32_e32 v65, 1, v151
	v_sub_u32_e32 v64, v64, v65
	v_mov_b32_e32 v65, v12
	v_lshl_add_u64 v[62:63], v[0:1], 0, v[64:65]
	v_mul_f32_e32 v2, v30, v9
	v_bfe_u32 v3, v2, 16, 1
	v_add3_u32 v2, v2, v3, s97
	ds_write_b16_d16_hi v60, v2 offset:0
	v_mul_f32_e32 v2, v14, v9
	v_bfe_u32 v3, v2, 16, 1
	v_add3_u32 v2, v2, v3, s97
	ds_write_b16_d16_hi v60, v2 offset:64
	v_mul_f32_e32 v2, v31, v10
	v_bfe_u32 v3, v2, 16, 1
	v_add3_u32 v2, v2, v3, s97
	ds_write_b16_d16_hi v60, v2 offset:128
	v_mul_f32_e32 v2, v15, v10
	v_bfe_u32 v3, v2, 16, 1
	v_add3_u32 v2, v2, v3, s97
	ds_write_b16_d16_hi v60, v2 offset:192
	v_mul_f32_e32 v2, v32, v11
	v_bfe_u32 v3, v2, 16, 1
	v_add3_u32 v2, v2, v3, s97
	ds_write_b16_d16_hi v60, v2 offset:256
	v_mul_f32_e32 v2, v16, v11
	v_bfe_u32 v3, v2, 16, 1
	v_add3_u32 v2, v2, v3, s97
	ds_write_b16_d16_hi v60, v2 offset:320
	v_mul_f32_e32 v2, v33, v13
	v_bfe_u32 v3, v2, 16, 1
	v_add3_u32 v2, v2, v3, s97
	ds_write_b16_d16_hi v60, v2 offset:384
	v_mul_f32_e32 v2, v17, v13
	v_bfe_u32 v3, v2, 16, 1
	v_add3_u32 v2, v2, v3, s97
	ds_write_b16_d16_hi v60, v2 offset:448
	v_mul_f32_e32 v2, v34, v46
	v_bfe_u32 v3, v2, 16, 1
	s_movk_i32 s0, 0x2000
	v_add3_u32 v4, v2, v3, s97
	v_add_co_u32_e32 v2, vcc, s0, v0
	s_movk_i32 s0, 0x6000
	s_nop 0
	v_addc_co_u32_e32 v3, vcc, 0, v1, vcc
	ds_write_b16_d16_hi v60, v4 offset:1024
	v_mul_f32_e32 v4, v18, v46
	v_bfe_u32 v5, v4, 16, 1
	v_add3_u32 v4, v4, v5, s97
	ds_write_b16_d16_hi v60, v4 offset:1088
	v_mul_f32_e32 v4, v35, v47
	v_bfe_u32 v5, v4, 16, 1
	v_add3_u32 v4, v4, v5, s97
	ds_write_b16_d16_hi v60, v4 offset:1152
	v_mul_f32_e32 v4, v19, v47
	v_bfe_u32 v5, v4, 16, 1
	v_add3_u32 v4, v4, v5, s97
	ds_write_b16_d16_hi v60, v4 offset:1216
	v_mul_f32_e32 v4, v36, v48
	v_bfe_u32 v5, v4, 16, 1
	v_add3_u32 v4, v4, v5, s97
	ds_write_b16_d16_hi v60, v4 offset:1280
	v_mul_f32_e32 v4, v20, v48
	v_bfe_u32 v5, v4, 16, 1
	v_add3_u32 v4, v4, v5, s97
	ds_write_b16_d16_hi v60, v4 offset:1344
	v_mul_f32_e32 v4, v37, v49
	v_bfe_u32 v5, v4, 16, 1
	v_add3_u32 v4, v4, v5, s97
	ds_write_b16_d16_hi v60, v4 offset:1408
	v_mul_f32_e32 v4, v21, v49
	v_bfe_u32 v5, v4, 16, 1
	v_add3_u32 v4, v4, v5, s97
	ds_write_b16_d16_hi v60, v4 offset:1472
	v_mul_f32_e32 v2, v38, v8
	v_bfe_u32 v3, v2, 16, 1
	v_add3_u32 v4, v2, v3, s97
	v_add_co_u32_e32 v2, vcc, s71, v0
	v_rcp_f32_e32 v6, v6
	s_nop 0
	v_addc_co_u32_e32 v3, vcc, 0, v1, vcc
	ds_write_b16_d16_hi v60, v4 offset:2048
	v_mul_f32_e32 v4, v22, v8
	v_bfe_u32 v5, v4, 16, 1
	v_add3_u32 v4, v4, v5, s97
	ds_write_b16_d16_hi v60, v4 offset:2112
	v_mul_f32_e32 v4, v39, v50
	v_bfe_u32 v5, v4, 16, 1
	v_add3_u32 v4, v4, v5, s97
	ds_write_b16_d16_hi v60, v4 offset:2176
	v_mul_f32_e32 v4, v23, v50
	v_bfe_u32 v5, v4, 16, 1
	v_add3_u32 v4, v4, v5, s97
	ds_write_b16_d16_hi v60, v4 offset:2240
	v_mul_f32_e32 v4, v40, v51
	v_bfe_u32 v5, v4, 16, 1
	v_add3_u32 v4, v4, v5, s97
	ds_write_b16_d16_hi v60, v4 offset:2304
	v_mul_f32_e32 v4, v24, v51
	v_bfe_u32 v5, v4, 16, 1
	v_add3_u32 v4, v4, v5, s97
	ds_write_b16_d16_hi v60, v4 offset:2368
	v_mul_f32_e32 v4, v41, v52
	v_bfe_u32 v5, v4, 16, 1
	v_add3_u32 v4, v4, v5, s97
	ds_write_b16_d16_hi v60, v4 offset:2432
	v_mul_f32_e32 v4, v25, v52
	v_bfe_u32 v5, v4, 16, 1
	v_add3_u32 v4, v4, v5, s97
	ds_write_b16_d16_hi v60, v4 offset:2496
	v_mul_f32_e32 v2, v42, v53
	v_bfe_u32 v3, v2, 16, 1
	v_add_co_u32_e32 v0, vcc, s0, v0
	v_add3_u32 v2, v2, v3, s97
	s_nop 0
	v_addc_co_u32_e32 v1, vcc, 0, v1, vcc
	ds_write_b16_d16_hi v60, v2 offset:3072
	v_mul_f32_e32 v2, v26, v53
	v_bfe_u32 v3, v2, 16, 1
	v_add3_u32 v2, v2, v3, s97
	ds_write_b16_d16_hi v60, v2 offset:3136
	v_mul_f32_e32 v2, v43, v54
	v_bfe_u32 v3, v2, 16, 1
	v_add3_u32 v2, v2, v3, s97
	ds_write_b16_d16_hi v60, v2 offset:3200
	v_mul_f32_e32 v2, v27, v54
	v_bfe_u32 v3, v2, 16, 1
	v_add3_u32 v2, v2, v3, s97
	ds_write_b16_d16_hi v60, v2 offset:3264
	v_mul_f32_e32 v2, v44, v6
	v_bfe_u32 v3, v2, 16, 1
	v_rcp_f32_e32 v7, v7
	v_add3_u32 v2, v2, v3, s97
	ds_write_b16_d16_hi v60, v2 offset:3328
	v_mul_f32_e32 v2, v28, v6
	v_bfe_u32 v3, v2, 16, 1
	v_add3_u32 v2, v2, v3, s97
	ds_write_b16_d16_hi v60, v2 offset:3392
	v_mul_f32_e32 v2, v45, v7
	v_bfe_u32 v3, v2, 16, 1
	v_add3_u32 v2, v2, v3, s97
	ds_write_b16_d16_hi v60, v2 offset:3456
	v_mul_f32_e32 v2, v29, v7
	v_bfe_u32 v3, v2, 16, 1
	s_add_i32 s34, s34, s60
	v_readlane_b32 s0, v255, 19
	v_add3_u32 v2, v2, v3, s97
	s_cmp_lt_i32 s34, s0
	ds_write_b16_d16_hi v60, v2 offset:3520
	s_waitcnt lgkmcnt(0)
	ds_read_b128 v[14:17], v61
	ds_read_b128 v[18:21], v61 offset:1024
	ds_read_b128 v[22:25], v61 offset:2048
	ds_read_b128 v[26:29], v61 offset:3072
	v_add_co_u32_e32 v66, vcc, 0x2000, v62
	s_nop 1
	v_addc_co_u32_e32 v67, vcc, 0, v63, vcc
	v_add_co_u32_e32 v68, vcc, 0x4000, v62
	s_nop 1
	v_addc_co_u32_e32 v69, vcc, 0, v63, vcc
	v_add_co_u32_e32 v70, vcc, 0x6000, v62
	s_nop 1
	v_addc_co_u32_e32 v71, vcc, 0, v63, vcc
	s_waitcnt lgkmcnt(3)
	global_store_dwordx4 v[62:63], v[14:17], off
	s_waitcnt lgkmcnt(2)
	global_store_dwordx4 v[66:67], v[18:21], off
	s_waitcnt lgkmcnt(1)
	global_store_dwordx4 v[68:69], v[22:25], off
	s_waitcnt lgkmcnt(0)
	global_store_dwordx4 v[70:71], v[26:29], off
	s_barrier
	s_cbranch_scc0 .LBB0_1183
